# attention K/V-tile loop hand-scheduled: LDS fragment reads 8 ahead through a register ring, trimmed softmax VALU
# speedup vs baseline: 1.0083x; 1.0083x over previous
.LBB0_366:
	s_cmp_gt_i32 s43, s11
	s_cselect_b64 s[22:23], -1, 0
	s_xor_b64 s[74:75], s[30:31], -1
	s_or_b64 s[22:23], s[74:75], s[22:23]
	s_and_b64 vcc, exec, s[22:23]
	s_cbranch_vccnz .LBB0_380
	s_andn2_b64 vcc, exec, s[36:37]
	v_add_u32_e32 v209, s18, v187
	s_cbranch_vccnz .Ld_nonstag_k
	s_cmp_lg_u32 s65, 0
	s_cselect_b32 s19, s19, 0x10000
	v_add_u32_e32 v208, s19, v186
	s_setprio 1
	ds_read_b128 v[220:223], v208
	ds_read_b128 v[224:227], v208 offset:1024
	ds_read_b128 v[228:231], v208 offset:2048
	ds_read_b128 v[232:235], v208 offset:3072
	ds_read_b128 v[236:239], v208 offset:4096
	ds_read_b128 v[240:243], v208 offset:5120
	ds_read_b128 v[244:247], v208 offset:6144
	ds_read_b128 v[248:251], v208 offset:7168
	s_waitcnt lgkmcnt(7)
	v_mfma_f32_16x16x32_bf16 v[64:67], v[220:223], v[122:125], v[64:67]
	v_mfma_f32_16x16x32_bf16 v[60:63], v[220:223], v[130:133], v[60:63]
	ds_read_b128 v[220:223], v208 offset:8192
	s_waitcnt lgkmcnt(7)
	v_mfma_f32_16x16x32_bf16 v[64:67], v[224:227], v[118:121], v[64:67]
	v_mfma_f32_16x16x32_bf16 v[60:63], v[224:227], v[126:129], v[60:63]
	ds_read_b128 v[224:227], v208 offset:9216
	s_waitcnt lgkmcnt(7)
	v_mfma_f32_16x16x32_bf16 v[56:59], v[228:231], v[122:125], v[56:59]
	v_mfma_f32_16x16x32_bf16 v[52:55], v[228:231], v[130:133], v[52:55]
	ds_read_b128 v[228:231], v208 offset:10240
	s_waitcnt lgkmcnt(7)
	v_mfma_f32_16x16x32_bf16 v[56:59], v[232:235], v[118:121], v[56:59]
	v_mfma_f32_16x16x32_bf16 v[52:55], v[232:235], v[126:129], v[52:55]
	ds_read_b128 v[232:235], v208 offset:11264
	s_waitcnt lgkmcnt(7)
	v_mfma_f32_16x16x32_bf16 v[48:51], v[236:239], v[122:125], v[48:51]
	v_mfma_f32_16x16x32_bf16 v[44:47], v[236:239], v[130:133], v[44:47]
	ds_read_b128 v[236:239], v208 offset:12288
	s_waitcnt lgkmcnt(7)
	v_mfma_f32_16x16x32_bf16 v[48:51], v[240:243], v[118:121], v[48:51]
	v_mfma_f32_16x16x32_bf16 v[44:47], v[240:243], v[126:129], v[44:47]
	ds_read_b128 v[240:243], v208 offset:13312
	s_waitcnt lgkmcnt(7)
	v_mfma_f32_16x16x32_bf16 v[40:43], v[244:247], v[122:125], v[40:43]
	v_mfma_f32_16x16x32_bf16 v[36:39], v[244:247], v[130:133], v[36:39]
	ds_read_b128 v[244:247], v208 offset:14336
	s_waitcnt lgkmcnt(7)
	v_mfma_f32_16x16x32_bf16 v[40:43], v[248:251], v[118:121], v[40:43]
	v_mfma_f32_16x16x32_bf16 v[36:39], v[248:251], v[126:129], v[36:39]
	ds_read_b128 v[248:251], v208 offset:15360
	s_waitcnt lgkmcnt(7)
	v_mfma_f32_16x16x32_bf16 v[32:35], v[220:223], v[122:125], v[32:35]
	v_mfma_f32_16x16x32_bf16 v[28:31], v[220:223], v[130:133], v[28:31]
	ds_read_b128 v[220:223], v209
	s_waitcnt lgkmcnt(7)
	v_mfma_f32_16x16x32_bf16 v[32:35], v[224:227], v[118:121], v[32:35]
	v_mfma_f32_16x16x32_bf16 v[28:31], v[224:227], v[126:129], v[28:31]
	ds_read_b128 v[224:227], v209 offset:1024
	s_waitcnt lgkmcnt(7)
	v_mfma_f32_16x16x32_bf16 v[24:27], v[228:231], v[122:125], v[24:27]
	v_mfma_f32_16x16x32_bf16 v[20:23], v[228:231], v[130:133], v[20:23]
	ds_read_b128 v[228:231], v209 offset:2048
	s_waitcnt lgkmcnt(7)
	v_mfma_f32_16x16x32_bf16 v[24:27], v[232:235], v[118:121], v[24:27]
	v_mfma_f32_16x16x32_bf16 v[20:23], v[232:235], v[126:129], v[20:23]
	ds_read_b128 v[232:235], v209 offset:3072
	s_waitcnt lgkmcnt(7)
	v_mfma_f32_16x16x32_bf16 v[16:19], v[236:239], v[122:125], v[16:19]
	v_mfma_f32_16x16x32_bf16 v[12:15], v[236:239], v[130:133], v[12:15]
	ds_read_b128 v[236:239], v209 offset:4096
	s_waitcnt lgkmcnt(7)
	v_mfma_f32_16x16x32_bf16 v[16:19], v[240:243], v[118:121], v[16:19]
	v_mfma_f32_16x16x32_bf16 v[12:15], v[240:243], v[126:129], v[12:15]
	ds_read_b128 v[240:243], v209 offset:5120
	s_waitcnt lgkmcnt(7)
	v_mfma_f32_16x16x32_bf16 v[72:75], v[244:247], v[122:125], v[72:75]
	v_mfma_f32_16x16x32_bf16 v[68:71], v[244:247], v[130:133], v[68:71]
	ds_read_b128 v[244:247], v209 offset:6144
	s_waitcnt lgkmcnt(7)
	v_mfma_f32_16x16x32_bf16 v[72:75], v[248:251], v[118:121], v[72:75]
	v_mfma_f32_16x16x32_bf16 v[68:71], v[248:251], v[126:129], v[68:71]
	ds_read_b128 v[248:251], v209 offset:7168
	s_setprio 0
	s_branch .Ld_qk
.Ld_nonstag_k:
	ds_read_b128 v[220:223], v209
	ds_read_b128 v[224:227], v209 offset:1024
	ds_read_b128 v[228:231], v209 offset:2048
	ds_read_b128 v[232:235], v209 offset:3072
	ds_read_b128 v[236:239], v209 offset:4096
	ds_read_b128 v[240:243], v209 offset:5120
	ds_read_b128 v[244:247], v209 offset:6144
	ds_read_b128 v[248:251], v209 offset:7168
.Ld_qk:
	s_waitcnt lgkmcnt(7)
	v_mfma_f32_16x16x32_bf16 v[142:145], v[220:223], v[76:79], v[100:103]
	v_mfma_f32_16x16x32_bf16 v[134:137], v[220:223], v[84:87], v[100:103]
	s_waitcnt lgkmcnt(6)
	v_mfma_f32_16x16x32_bf16 v[142:145], v[224:227], v[80:83], v[142:145]
	v_mfma_f32_16x16x32_bf16 v[134:137], v[224:227], v[88:91], v[134:137]
	s_waitcnt lgkmcnt(5)
	v_mfma_f32_16x16x32_bf16 v[122:125], v[228:231], v[76:79], v[106:109]
	v_mfma_f32_16x16x32_bf16 v[130:133], v[228:231], v[84:87], v[106:109]
	s_waitcnt lgkmcnt(4)
	v_mfma_f32_16x16x32_bf16 v[122:125], v[232:235], v[80:83], v[122:125]
	v_mfma_f32_16x16x32_bf16 v[130:133], v[232:235], v[88:91], v[130:133]
	s_waitcnt lgkmcnt(3)
	v_mfma_f32_16x16x32_bf16 v[118:121], v[236:239], v[76:79], v[114:117]
	v_mfma_f32_16x16x32_bf16 v[126:129], v[236:239], v[84:87], v[114:117]
	s_waitcnt lgkmcnt(2)
	v_mfma_f32_16x16x32_bf16 v[118:121], v[240:243], v[80:83], v[118:121]
	v_mfma_f32_16x16x32_bf16 v[126:129], v[240:243], v[88:91], v[126:129]
	s_waitcnt lgkmcnt(1)
	v_mfma_f32_16x16x32_bf16 v[146:149], v[244:247], v[76:79], v[92:95]
	v_mfma_f32_16x16x32_bf16 v[138:141], v[244:247], v[84:87], v[92:95]
	s_waitcnt lgkmcnt(0)
	v_mfma_f32_16x16x32_bf16 v[146:149], v[248:251], v[80:83], v[146:149]
	v_mfma_f32_16x16x32_bf16 v[138:141], v[248:251], v[88:91], v[138:141]
	s_and_b64 vcc, exec, s[40:41]
	s_cbranch_vccnz .Ld_sm
	v_add_u32_e32 v208, s65, v186
	ds_read_b128 v[220:223], v208 offset:32768
	ds_read_b128 v[224:227], v208 offset:33792
	ds_read_b128 v[228:231], v208 offset:34816
	ds_read_b128 v[232:235], v208 offset:35840
	ds_read_b128 v[236:239], v208 offset:36864
	ds_read_b128 v[240:243], v208 offset:37888
	ds_read_b128 v[244:247], v208 offset:38912
	ds_read_b128 v[248:251], v208 offset:39936
.Ld_sm:
	s_add_i32 s18, s60, s43
	v_add_u32_e32 v188, s62, v169
	s_cmp_lg_u32 s18, 1
	s_cbranch_scc1 .Ld_nomask
	v_add_u32_e32 v0, 0xfffff800, v188
	v_add_u32_e32 v189, v0, v97
	v_add_u32_e32 v190, v0, v98
	v_add_u32_e32 v191, v0, v99
	v_add_u32_e32 v192, v0, v96
	v_max_i32_e32 v190, 0, v190
	v_max_i32_e32 v189, 0, v189
	v_max_i32_e32 v192, 0, v192
	v_max_i32_e32 v193, 0, v191
	v_cvt_f32_u32_e32 v191, v189
	v_cvt_f32_u32_e32 v190, v190
	v_cvt_f32_u32_e32 v193, v193
	v_cvt_f32_u32_e32 v192, v192
	s_xor_b32 s19, s59, 0x80000000
	s_xor_b32 s18, s55, 0x80000000
	v_pk_fma_f32 v[142:143], s[38:39], v[190:191], v[142:143] neg_lo:[1,0,0] neg_hi:[1,0,0]
	v_add_u32_e32 v189, v0, v3
	v_add_u32_e32 v190, v0, v2
	v_pk_fma_f32 v[144:145], s[18:19], v[192:193], v[144:145]
	v_add_u32_e32 v191, v0, v105
	v_add_u32_e32 v192, v0, v104
	v_max_i32_e32 v190, 0, v190
	v_max_i32_e32 v189, 0, v189
	v_max_i32_e32 v192, 0, v192
	v_max_i32_e32 v193, 0, v191
	v_cvt_f32_u32_e32 v191, v189
	v_cvt_f32_u32_e32 v190, v190
	v_cvt_f32_u32_e32 v193, v193
	v_cvt_f32_u32_e32 v192, v192
	v_add_u32_e32 v189, v0, v111
	v_pk_fma_f32 v[122:123], s[38:39], v[190:191], v[122:123] neg_lo:[1,0,0] neg_hi:[1,0,0]
	v_add_u32_e32 v190, v0, v110
	v_pk_fma_f32 v[124:125], s[18:19], v[192:193], v[124:125]
	v_add_u32_e32 v191, v0, v113
	v_add_u32_e32 v192, v0, v112
	v_max_i32_e32 v190, 0, v190
	v_max_i32_e32 v189, 0, v189
	v_max_i32_e32 v192, 0, v192
	v_max_i32_e32 v193, 0, v191
	v_cvt_f32_u32_e32 v191, v189
	v_cvt_f32_u32_e32 v190, v190
	v_cvt_f32_u32_e32 v193, v193
	v_cvt_f32_u32_e32 v192, v192
	v_add_u32_e32 v189, v0, v163
	v_pk_fma_f32 v[118:119], s[38:39], v[190:191], v[118:119] neg_lo:[1,0,0] neg_hi:[1,0,0]
	v_add_u32_e32 v190, v0, v170
	v_add_u32_e32 v191, v0, v171
	v_add_u32_e32 v0, v0, v172
	v_pk_fma_f32 v[120:121], s[18:19], v[192:193], v[120:121]
	v_max_i32_e32 v0, 0, v0
	v_max_i32_e32 v192, 0, v191
	v_max_i32_e32 v190, 0, v190
	v_max_i32_e32 v189, 0, v189
	v_cvt_f32_u32_e32 v191, v189
	v_cvt_f32_u32_e32 v190, v190
	v_cvt_f32_u32_e32 v193, v192
	v_cvt_f32_u32_e32 v192, v0
	v_pk_fma_f32 v[146:147], s[38:39], v[190:191], v[146:147] neg_lo:[1,0,0] neg_hi:[1,0,0]
	v_pk_fma_f32 v[148:149], s[18:19], v[192:193], v[148:149]
	v_add_u32_e32 v188, 0xfffff7f0, v188
	v_add_u32_e32 v190, v188, v97
	v_add_u32_e32 v191, v188, v98
	v_add_u32_e32 v192, v188, v99
	v_add_u32_e32 v193, v188, v96
	v_max_i32_e32 v195, 0, v193
	v_max_i32_e32 v192, 0, v192
	v_max_i32_e32 v193, 0, v191
	v_max_i32_e32 v190, 0, v190
	v_cvt_f32_u32_e32 v191, v190
	v_cvt_f32_u32_e32 v190, v193
	v_cvt_f32_u32_e32 v193, v192
	v_cvt_f32_u32_e32 v192, v195
	s_xor_b32 s19, s59, 0x80000000
	s_xor_b32 s18, s55, 0x80000000
	v_pk_fma_f32 v[134:135], s[38:39], v[190:191], v[134:135] neg_lo:[1,0,0] neg_hi:[1,0,0]
	v_pk_fma_f32 v[136:137], s[18:19], v[192:193], v[136:137]
	v_add_u32_e32 v190, v188, v3
	v_add_u32_e32 v191, v188, v2
	v_add_u32_e32 v192, v188, v105
	v_add_u32_e32 v193, v188, v104
	v_max_i32_e32 v195, 0, v193
	v_max_i32_e32 v192, 0, v192
	v_max_i32_e32 v193, 0, v191
	v_max_i32_e32 v190, 0, v190
	v_cvt_f32_u32_e32 v191, v190
	v_cvt_f32_u32_e32 v190, v193
	v_cvt_f32_u32_e32 v193, v192
	v_cvt_f32_u32_e32 v192, v195
	v_pk_fma_f32 v[130:131], s[38:39], v[190:191], v[130:131] neg_lo:[1,0,0] neg_hi:[1,0,0]
	v_add_u32_e32 v190, v188, v111
	v_pk_fma_f32 v[132:133], s[18:19], v[192:193], v[132:133]
	v_add_u32_e32 v191, v188, v110
	v_add_u32_e32 v192, v188, v113
	v_add_u32_e32 v193, v188, v112
	v_max_i32_e32 v195, 0, v193
	v_max_i32_e32 v192, 0, v192
	v_max_i32_e32 v193, 0, v191
	v_max_i32_e32 v190, 0, v190
	v_cvt_f32_u32_e32 v191, v190
	v_cvt_f32_u32_e32 v190, v193
	v_cvt_f32_u32_e32 v193, v192
	v_cvt_f32_u32_e32 v192, v195
	v_pk_fma_f32 v[126:127], s[38:39], v[190:191], v[126:127] neg_lo:[1,0,0] neg_hi:[1,0,0]
	v_add_u32_e32 v190, v188, v163
	v_pk_fma_f32 v[128:129], s[18:19], v[192:193], v[128:129]
	v_add_u32_e32 v191, v188, v170
	v_add_u32_e32 v192, v188, v171
	v_add_u32_e32 v188, v188, v172
	v_max_i32_e32 v188, 0, v188
	v_max_i32_e32 v192, 0, v192
	v_max_i32_e32 v193, 0, v191
	v_max_i32_e32 v190, 0, v190
	v_cvt_f32_u32_e32 v191, v190
	v_cvt_f32_u32_e32 v190, v193
	v_cvt_f32_u32_e32 v193, v192
	v_cvt_f32_u32_e32 v192, v188
	v_pk_fma_f32 v[138:139], s[38:39], v[190:191], v[138:139] neg_lo:[1,0,0] neg_hi:[1,0,0]
	v_pk_fma_f32 v[140:141], s[18:19], v[192:193], v[140:141]
.Ld_nomask:
	v_cvt_f32_u32_e32 v189, s62
	s_nop 0
	v_mul_f32_e32 v218, v168, v189
	v_max3_f32 v216, v142, v143, v144
	v_max3_f32 v216, v216, v145, v122
	v_max3_f32 v216, v216, v123, v124
	v_max3_f32 v216, v216, v125, v118
	v_max3_f32 v216, v216, v119, v120
	v_max3_f32 v216, v216, v121, v146
	v_max3_f32 v216, v216, v147, v148
	v_max_f32_e32 v216, v216, v149
	v_sub_f32_e32 v179, v179, v218
	v_mov_b32_e32 v217, v216
	s_nop 1
	v_permlane16_swap_b32_e32 v216, v217
	v_max_f32_e32 v216, v216, v217
	v_mov_b32_e32 v217, v216
	s_nop 1
	v_permlane32_swap_b32_e32 v216, v217
	v_max_f32_e32 v216, v216, v217
	v_add_f32_e32 v217, 0x41800000, v179
	v_mov_b32_e32 v210, 1.0
	v_cmp_le_f32_e32 vcc, v216, v217
	s_cmp_eq_u64 vcc, exec
	s_cbranch_scc1 .Ld_keep0
	v_max_f32_e32 v217, v179, v216
	v_sub_f32_e32 v210, v179, v217
	v_exp_f32_e32 v210, v210
	v_mov_b32_e32 v179, v217
	s_nop 0
	v_pk_mul_f32 v[66:67], v[66:67], v[210:211] op_sel_hi:[1,0]
	v_pk_mul_f32 v[64:65], v[64:65], v[210:211] op_sel_hi:[1,0]
	v_pk_mul_f32 v[58:59], v[58:59], v[210:211] op_sel_hi:[1,0]
	v_pk_mul_f32 v[56:57], v[56:57], v[210:211] op_sel_hi:[1,0]
	v_pk_mul_f32 v[50:51], v[50:51], v[210:211] op_sel_hi:[1,0]
	v_pk_mul_f32 v[48:49], v[48:49], v[210:211] op_sel_hi:[1,0]
	v_pk_mul_f32 v[42:43], v[42:43], v[210:211] op_sel_hi:[1,0]
	v_pk_mul_f32 v[40:41], v[40:41], v[210:211] op_sel_hi:[1,0]
	v_pk_mul_f32 v[34:35], v[34:35], v[210:211] op_sel_hi:[1,0]
	v_pk_mul_f32 v[32:33], v[32:33], v[210:211] op_sel_hi:[1,0]
	v_pk_mul_f32 v[26:27], v[26:27], v[210:211] op_sel_hi:[1,0]
	v_pk_mul_f32 v[24:25], v[24:25], v[210:211] op_sel_hi:[1,0]
	v_pk_mul_f32 v[18:19], v[18:19], v[210:211] op_sel_hi:[1,0]
	v_pk_mul_f32 v[16:17], v[16:17], v[210:211] op_sel_hi:[1,0]
	v_pk_mul_f32 v[74:75], v[74:75], v[210:211] op_sel_hi:[1,0]
	v_pk_mul_f32 v[72:73], v[72:73], v[210:211] op_sel_hi:[1,0]
.Ld_keep0:
	v_sub_f32_e32 v142, v142, v179
	v_sub_f32_e32 v143, v143, v179
	v_sub_f32_e32 v144, v144, v179
	v_sub_f32_e32 v145, v145, v179
	v_sub_f32_e32 v122, v122, v179
	v_sub_f32_e32 v123, v123, v179
	v_sub_f32_e32 v124, v124, v179
	v_sub_f32_e32 v125, v125, v179
	v_sub_f32_e32 v118, v118, v179
	v_sub_f32_e32 v119, v119, v179
	v_sub_f32_e32 v120, v120, v179
	v_sub_f32_e32 v121, v121, v179
	v_sub_f32_e32 v146, v146, v179
	v_sub_f32_e32 v147, v147, v179
	v_sub_f32_e32 v148, v148, v179
	v_sub_f32_e32 v149, v149, v179
	v_exp_f32_e32 v142, v142
	v_exp_f32_e32 v143, v143
	v_exp_f32_e32 v144, v144
	v_add_f32_e32 v214, 0, v142
	v_exp_f32_e32 v145, v145
	v_add_f32_e32 v214, v143, v214
	v_exp_f32_e32 v122, v122
	v_add_f32_e32 v214, v144, v214
	v_exp_f32_e32 v123, v123
	v_add_f32_e32 v214, v145, v214
	v_exp_f32_e32 v124, v124
	v_add_f32_e32 v214, v122, v214
	v_exp_f32_e32 v125, v125
	v_add_f32_e32 v214, v123, v214
	v_exp_f32_e32 v118, v118
	v_add_f32_e32 v214, v124, v214
	v_exp_f32_e32 v119, v119
	v_add_f32_e32 v214, v125, v214
	v_exp_f32_e32 v120, v120
	v_add_f32_e32 v214, v118, v214
	v_exp_f32_e32 v121, v121
	v_add_f32_e32 v214, v119, v214
	v_exp_f32_e32 v146, v146
	v_add_f32_e32 v214, v120, v214
	v_exp_f32_e32 v147, v147
	v_add_f32_e32 v214, v121, v214
	v_exp_f32_e32 v148, v148
	v_add_f32_e32 v214, v146, v214
	v_exp_f32_e32 v149, v149
	v_add_f32_e32 v214, v147, v214
	v_add_f32_e32 v214, v148, v214
	v_add_f32_e32 v179, v218, v179
	v_add_f32_e32 v214, v149, v214
	v_fmac_f32_e32 v214, v175, v210
	v_cvt_pk_bf16_f32 v125, v124, v125
	v_cvt_pk_bf16_f32 v124, v122, v123
	v_cvt_pk_bf16_f32 v122, v142, v143
	v_cvt_pk_bf16_f32 v123, v144, v145
	v_cvt_pk_bf16_f32 v118, v118, v119
	v_cvt_pk_bf16_f32 v119, v120, v121
	v_cvt_pk_bf16_f32 v120, v146, v147
	v_cvt_pk_bf16_f32 v121, v148, v149
	v_mov_b32_e32 v175, v214
	v_max3_f32 v216, v134, v135, v136
	v_max3_f32 v216, v216, v137, v130
	v_max3_f32 v216, v216, v131, v132
	v_max3_f32 v216, v216, v133, v126
	v_max3_f32 v216, v216, v127, v128
	v_max3_f32 v216, v216, v129, v138
	v_max3_f32 v216, v216, v139, v140
	v_max_f32_e32 v216, v216, v141
	v_sub_f32_e32 v178, v178, v218
	v_mov_b32_e32 v217, v216
	s_nop 1
	v_permlane16_swap_b32_e32 v216, v217
	v_max_f32_e32 v216, v216, v217
	v_mov_b32_e32 v217, v216
	s_nop 1
	v_permlane32_swap_b32_e32 v216, v217
	v_max_f32_e32 v216, v216, v217
	v_add_f32_e32 v217, 0x41800000, v178
	v_mov_b32_e32 v212, 1.0
	v_cmp_le_f32_e32 vcc, v216, v217
	s_cmp_eq_u64 vcc, exec
	s_cbranch_scc1 .Ld_keep1
	v_max_f32_e32 v217, v178, v216
	v_sub_f32_e32 v212, v178, v217
	v_exp_f32_e32 v212, v212
	v_mov_b32_e32 v178, v217
	s_nop 0
	v_pk_mul_f32 v[62:63], v[62:63], v[212:213] op_sel_hi:[1,0]
	v_pk_mul_f32 v[60:61], v[60:61], v[212:213] op_sel_hi:[1,0]
	v_pk_mul_f32 v[54:55], v[54:55], v[212:213] op_sel_hi:[1,0]
	v_pk_mul_f32 v[52:53], v[52:53], v[212:213] op_sel_hi:[1,0]
	v_pk_mul_f32 v[46:47], v[46:47], v[212:213] op_sel_hi:[1,0]
	v_pk_mul_f32 v[44:45], v[44:45], v[212:213] op_sel_hi:[1,0]
	v_pk_mul_f32 v[38:39], v[38:39], v[212:213] op_sel_hi:[1,0]
	v_pk_mul_f32 v[36:37], v[36:37], v[212:213] op_sel_hi:[1,0]
	v_pk_mul_f32 v[30:31], v[30:31], v[212:213] op_sel_hi:[1,0]
	v_pk_mul_f32 v[28:29], v[28:29], v[212:213] op_sel_hi:[1,0]
	v_pk_mul_f32 v[22:23], v[22:23], v[212:213] op_sel_hi:[1,0]
	v_pk_mul_f32 v[20:21], v[20:21], v[212:213] op_sel_hi:[1,0]
	v_pk_mul_f32 v[14:15], v[14:15], v[212:213] op_sel_hi:[1,0]
	v_pk_mul_f32 v[12:13], v[12:13], v[212:213] op_sel_hi:[1,0]
	v_pk_mul_f32 v[70:71], v[70:71], v[212:213] op_sel_hi:[1,0]
	v_pk_mul_f32 v[68:69], v[68:69], v[212:213] op_sel_hi:[1,0]
.Ld_keep1:
	v_sub_f32_e32 v134, v134, v178
	v_sub_f32_e32 v135, v135, v178
	v_sub_f32_e32 v136, v136, v178
	v_sub_f32_e32 v137, v137, v178
	v_sub_f32_e32 v130, v130, v178
	v_sub_f32_e32 v131, v131, v178
	v_sub_f32_e32 v132, v132, v178
	v_sub_f32_e32 v133, v133, v178
	v_sub_f32_e32 v126, v126, v178
	v_sub_f32_e32 v127, v127, v178
	v_sub_f32_e32 v128, v128, v178
	v_sub_f32_e32 v129, v129, v178
	v_sub_f32_e32 v138, v138, v178
	v_sub_f32_e32 v139, v139, v178
	v_sub_f32_e32 v140, v140, v178
	v_sub_f32_e32 v141, v141, v178
	v_exp_f32_e32 v134, v134
	v_exp_f32_e32 v135, v135
	v_exp_f32_e32 v136, v136
	v_add_f32_e32 v215, 0, v134
	v_exp_f32_e32 v137, v137
	v_add_f32_e32 v215, v135, v215
	v_exp_f32_e32 v130, v130
	v_add_f32_e32 v215, v136, v215
	v_exp_f32_e32 v131, v131
	v_add_f32_e32 v215, v137, v215
	v_exp_f32_e32 v132, v132
	v_add_f32_e32 v215, v130, v215
	v_exp_f32_e32 v133, v133
	v_add_f32_e32 v215, v131, v215
	v_exp_f32_e32 v126, v126
	v_add_f32_e32 v215, v132, v215
	v_exp_f32_e32 v127, v127
	v_add_f32_e32 v215, v133, v215
	v_exp_f32_e32 v128, v128
	v_add_f32_e32 v215, v126, v215
	v_exp_f32_e32 v129, v129
	v_add_f32_e32 v215, v127, v215
	v_exp_f32_e32 v138, v138
	v_add_f32_e32 v215, v128, v215
	v_exp_f32_e32 v139, v139
	v_add_f32_e32 v215, v129, v215
	v_exp_f32_e32 v140, v140
	v_add_f32_e32 v215, v138, v215
	v_exp_f32_e32 v141, v141
	v_add_f32_e32 v215, v139, v215
	v_add_f32_e32 v215, v140, v215
	v_add_f32_e32 v178, v218, v178
	v_add_f32_e32 v215, v141, v215
	v_fmac_f32_e32 v215, v174, v212
	v_cvt_pk_bf16_f32 v133, v132, v133
	v_cvt_pk_bf16_f32 v132, v130, v131
	v_cvt_pk_bf16_f32 v130, v134, v135
	v_cvt_pk_bf16_f32 v131, v136, v137
	v_cvt_pk_bf16_f32 v126, v126, v127
	v_cvt_pk_bf16_f32 v127, v128, v129
	v_cvt_pk_bf16_f32 v128, v138, v139
	v_cvt_pk_bf16_f32 v129, v140, v141
	v_mov_b32_e32 v174, v215
	s_and_b64 vcc, exec, s[40:41]
	s_cbranch_vccnz .LBB0_380
	s_setprio 1
	s_waitcnt lgkmcnt(7)
	v_mfma_f32_16x16x32_bf16 v[64:67], v[220:223], v[122:125], v[64:67]
	v_mfma_f32_16x16x32_bf16 v[60:63], v[220:223], v[130:133], v[60:63]
	ds_read_b128 v[220:223], v208 offset:40960
	s_waitcnt lgkmcnt(7)
	v_mfma_f32_16x16x32_bf16 v[64:67], v[224:227], v[118:121], v[64:67]
	v_mfma_f32_16x16x32_bf16 v[60:63], v[224:227], v[126:129], v[60:63]
	ds_read_b128 v[224:227], v208 offset:41984
	s_waitcnt lgkmcnt(7)
	v_mfma_f32_16x16x32_bf16 v[56:59], v[228:231], v[122:125], v[56:59]
	v_mfma_f32_16x16x32_bf16 v[52:55], v[228:231], v[130:133], v[52:55]
	ds_read_b128 v[228:231], v208 offset:43008
	s_waitcnt lgkmcnt(7)
	v_mfma_f32_16x16x32_bf16 v[56:59], v[232:235], v[118:121], v[56:59]
	v_mfma_f32_16x16x32_bf16 v[52:55], v[232:235], v[126:129], v[52:55]
	ds_read_b128 v[232:235], v208 offset:44032
	s_waitcnt lgkmcnt(7)
	v_mfma_f32_16x16x32_bf16 v[48:51], v[236:239], v[122:125], v[48:51]
	v_mfma_f32_16x16x32_bf16 v[44:47], v[236:239], v[130:133], v[44:47]
	ds_read_b128 v[236:239], v208 offset:45056
	s_waitcnt lgkmcnt(7)
	v_mfma_f32_16x16x32_bf16 v[48:51], v[240:243], v[118:121], v[48:51]
	v_mfma_f32_16x16x32_bf16 v[44:47], v[240:243], v[126:129], v[44:47]
	ds_read_b128 v[240:243], v208 offset:46080
	s_waitcnt lgkmcnt(7)
	v_mfma_f32_16x16x32_bf16 v[40:43], v[244:247], v[122:125], v[40:43]
	v_mfma_f32_16x16x32_bf16 v[36:39], v[244:247], v[130:133], v[36:39]
	ds_read_b128 v[244:247], v208 offset:47104
	s_waitcnt lgkmcnt(7)
	v_mfma_f32_16x16x32_bf16 v[40:43], v[248:251], v[118:121], v[40:43]
	v_mfma_f32_16x16x32_bf16 v[36:39], v[248:251], v[126:129], v[36:39]
	ds_read_b128 v[248:251], v208 offset:48128
	s_waitcnt lgkmcnt(7)
	v_mfma_f32_16x16x32_bf16 v[32:35], v[220:223], v[122:125], v[32:35]
	v_mfma_f32_16x16x32_bf16 v[28:31], v[220:223], v[130:133], v[28:31]
	s_waitcnt lgkmcnt(6)
	v_mfma_f32_16x16x32_bf16 v[32:35], v[224:227], v[118:121], v[32:35]
	v_mfma_f32_16x16x32_bf16 v[28:31], v[224:227], v[126:129], v[28:31]
	s_waitcnt lgkmcnt(5)
	v_mfma_f32_16x16x32_bf16 v[24:27], v[228:231], v[122:125], v[24:27]
	v_mfma_f32_16x16x32_bf16 v[20:23], v[228:231], v[130:133], v[20:23]
	s_waitcnt lgkmcnt(4)
	v_mfma_f32_16x16x32_bf16 v[24:27], v[232:235], v[118:121], v[24:27]
	v_mfma_f32_16x16x32_bf16 v[20:23], v[232:235], v[126:129], v[20:23]
	s_waitcnt lgkmcnt(3)
	v_mfma_f32_16x16x32_bf16 v[16:19], v[236:239], v[122:125], v[16:19]
	v_mfma_f32_16x16x32_bf16 v[12:15], v[236:239], v[130:133], v[12:15]
	s_waitcnt lgkmcnt(2)
	v_mfma_f32_16x16x32_bf16 v[16:19], v[240:243], v[118:121], v[16:19]
	v_mfma_f32_16x16x32_bf16 v[12:15], v[240:243], v[126:129], v[12:15]
	s_waitcnt lgkmcnt(1)
	v_mfma_f32_16x16x32_bf16 v[72:75], v[244:247], v[122:125], v[72:75]
	v_mfma_f32_16x16x32_bf16 v[68:71], v[244:247], v[130:133], v[68:71]
	s_waitcnt lgkmcnt(0)
	v_mfma_f32_16x16x32_bf16 v[72:75], v[248:251], v[118:121], v[72:75]
	v_mfma_f32_16x16x32_bf16 v[68:71], v[248:251], v[126:129], v[68:71]
	s_setprio 0
